# adds SGPR-base + 32-bit offset addressing for the c1 next-job prefetch loads (about 80 fewer VALU per job) on top of the previous best
# baseline (speedup 1.0000x reference)
; __device__ __forceinline__ void phase_hgrn_c1(const Params& p, int l, int bid, int nblk, LAS unsigned char* lds) {
;     ...
;         const int njob = c1_job(bid, kj + 1, nblk);
;         if (njob >= 0) {
;             const int nc = njob >> 3, nh = njob & 7, nr0 = nc * 64, nch = nh * 128 + k;
; #pragma unroll
;             for (int i = 0; i < 16; ++i) fr_[i] = p.P[(size_t)(nr0 + 16 * sg + i) * NIN + C_FC + nch];
; #pragma unroll
;             for (int i = 0; i < 2; ++i) { const int id = tid + 512 * i, s = id & 63, v8 = (id >> 6) * 8; vf_[i] = *(const bf16x8*)(p.P + (size_t)(nr0 + s) * NIN + C_IC + nh * 128 + v8); }
.LBB0_422:
	s_lshl_b32 s28, s44, 3
	s_lshl_b32 s29, s44, 7
	s_and_b32 s28, s28, 0x7fffffc0
	s_and_b32 s29, s29, 0x380
	s_add_u32 s98, s26, 0x2800
	s_addc_u32 s99, s27, 0
	v_or_b32_e32 v6, s29, v26
	v_add_u32_e32 v8, s28, v27
	v_mov_b64_e32 v[0:1], s[26:27]
	v_lshlrev_b32_e32 v6, 1, v6
	v_mov_b32_e32 v7, v5
	v_mul_lo_u32 v2, v8, s43
	v_add_u32_e32 v2, v2, v6
	global_load_ushort v28, v2, s[98:99]
	v_add_u32_e32 v2, 0x5800, v2
	global_load_ushort v29, v2, s[98:99]
	v_add_u32_e32 v2, 0x5800, v2
	global_load_ushort v30, v2, s[98:99]
	v_add_u32_e32 v2, 0x5800, v2
	global_load_ushort v31, v2, s[98:99]
	v_add_u32_e32 v2, 0x5800, v2
	global_load_ushort v32, v2, s[98:99]
	v_add_u32_e32 v2, 0x5800, v2
	global_load_ushort v33, v2, s[98:99]
	v_add_u32_e32 v2, 0x5800, v2
	global_load_ushort v35, v2, s[98:99]
	v_add_u32_e32 v2, 0x5800, v2
	global_load_ushort v38, v2, s[98:99]
	v_add_u32_e32 v2, 0x5800, v2
	global_load_ushort v44, v2, s[98:99]
	v_add_u32_e32 v2, 0x5800, v2
	global_load_ushort v45, v2, s[98:99]
	v_add_u32_e32 v2, 0x5800, v2
	global_load_ushort v46, v2, s[98:99]
	v_add_u32_e32 v2, 0x5800, v2
	global_load_ushort v47, v2, s[98:99]
	v_add_u32_e32 v2, 0x5800, v2
	global_load_ushort v48, v2, s[98:99]
	v_add_u32_e32 v2, 0x5800, v2
	global_load_ushort v49, v2, s[98:99]
	v_add_u32_e32 v2, 0x5800, v2
	global_load_ushort v50, v2, s[98:99]
	v_add_u32_e32 v2, 0x5800, v2
	global_load_ushort v51, v2, s[98:99]
	v_or_b32_e32 v2, s28, v34
	v_mad_u64_u32 v[0:1], s[46:47], v2, s43, v[0:1]
	s_lshl_b32 s28, s29, 1
	s_mov_b32 s29, s51
	v_lshl_add_u64 v[0:1], v[0:1], 0, s[28:29]
	v_lshl_add_u64 v[6:7], v[0:1], 0, s[62:63]
	v_lshl_add_u64 v[0:1], v[12:13], 1, v[6:7]
	v_lshl_add_u64 v[6:7], v[14:15], 1, v[6:7]
	global_load_dwordx4 v[0:3], v[0:1], off
	s_nop 0
	global_load_dwordx4 v[6:9], v[6:7], off
